# N=1024 GEMM phases: blocks 256..511 take the neighbouring n-tile (nt xor 1) of the same m-tile, so the two blocks resident on a CU stream different weight tiles
# speedup vs baseline: 1.1016x; 1.0006x over previous
; #define GA_LOAD(pr_) do { _Pragma("unroll") for (int i = 0; i < 4; ++i) ra[i] = *(const u32x4*)(Ab + (i * 32) * lda + (pr_) * 64); } while (0)
; #define GB_LOAD(kt_) do { const bfr* bk_ = Bb + (kt_) * NB * 32; \
;     _Pragma("unroll") for (int i = 0; i < 4; ++i) rb[i] = *(const u32x4*)(bk_ + (i * 64) * 32); } while (0)
; #define G_STORE(kt_) do { bfr* as_ = S0 + ((kt_) & 1) * GSTAGE; bfr* bs_ = as_ + 128 * 40; \
;     if (apar == ((kt_) & 1)) { _Pragma("unroll") for (int i = 0; i < 4; ++i) *(u32x4*)(as_ + asoff + i * 32 * 40) = ra[i]; } \
;     _Pragma("unroll") for (int i = 0; i < 4; ++i) *(u32x4*)(bs_ + bsoff + i * 64 * 40) = rb[i]; } while (0)
; template <int lda>
; DI void gemm_mainloop(const bfr* __restrict__ A, const bfr* __restrict__ Bt, int NB, int K, int m0, int n0, char* smem, f32x16 (&acc)[2][4]) {
;     ...
;   const int nk = K >> 5;
;   const int arow = tid >> 3, ac8 = tid & 7, apar = ac8 >> 2;
;   const bfr* Ab = A + (m0 + arow) * lda + ac8 * 8;
;   const int asoff = arow * 40 + (ac8 & 3) * 8;
;   const int brow = tid >> 2, bc4 = tid & 3;
;   const bfr* Bb = Bt + (n0 + brow) * 32 + bc4 * 8;
;   const int bsoff = brow * 40 + bc4 * 8;
;     ...
;   GA_LOAD(0);
;   GB_LOAD(0);
;   G_STORE(0);
;   GB_LOAD(1);
;   __syncthreads();
; template <bool FIRST, bool HAS_H>
; DI void phase_gemm_resid(const Params& p, const bfr* A, const bfr* Wt, const float* gnext, float* ss, char* smem) {
;     ...
;   for (int t0 = blockIdx.x; t0 < 128 * 4; t0 += gridDim.x) {
;     const int t = ((gridDim.x & 7) == 0) ? xcd_tile(t0, 4) : t0;
;     const int mt = t >> 2, nt = t & 3, m0 = mt * 128, n0 = nt * 256;
;     f32x16 acc[2][4];
;     gemm_mainloop<1024>(A, Wt, 1024, 1024, m0, n0, smem, acc);
.LBB0_843:
	s_lshl_b32 s5, s4, 5
	s_and_b32 s40, s5, 0xffffff80
	s_lshl_b32 s4, s4, 8
	s_and_b32 s39, s4, 0x300
	s_mov_b32 s41, 0
	s_mov_b64 s[24:25], 0
	s_cmp_lt_u32 s46, 0x100
	s_cselect_b32 s98, 0, 0x100
	s_xor_b32 s39, s39, s98
	s_lshl_b32 s98, s40, 11
	s_add_u32 s98, s12, s98
	s_addc_u32 s99, s13, 0
	s_lshl_b32 s100, s39, 6
	s_add_u32 s100, s6, s100
	s_addc_u32 s101, s7, 0
	v_writelane_b32 v207, s64, 0
	v_writelane_b32 v207, s65, 1
	v_writelane_b32 v207, s66, 2
	v_writelane_b32 v207, s67, 3
	v_writelane_b32 v207, s68, 4
	v_writelane_b32 v207, s69, 5
	v_writelane_b32 v207, s70, 6
	v_writelane_b32 v207, s71, 7
	v_writelane_b32 v207, s72, 8
	v_writelane_b32 v207, s73, 9
	v_writelane_b32 v207, s74, 10
	v_writelane_b32 v207, s75, 11
	v_writelane_b32 v207, s76, 12
	v_writelane_b32 v207, s77, 13
	v_writelane_b32 v207, s78, 14
	v_writelane_b32 v207, s79, 15
	s_mov_b32 s77, s40
	s_mov_b32 s78, s39
	v_lshrrev_b32_e32 v208, 6, v196
	v_and_b32_e32 v209, 63, v196
	v_readfirstlane_b32 s73, v208
	v_lshrrev_b32_e32 v210, 2, v209
	v_bfe_u32 v211, v209, 4, 2
	v_and_b32_e32 v208, 3, v209
	v_xor_b32_e32 v208, v208, v211
	v_lshlrev_b32_e32 v208, 4, v208
	v_lshl_add_u32 v188, v210, 11, v208
	v_add_u32_e32 v190, 0x8000, v188
	v_lshl_add_u32 v191, v210, 6, v208
	v_and_b32_e32 v210, 31, v209
	v_lshrrev_b32_e32 v211, 5, v209
	v_bfe_u32 v208, v209, 2, 2
	v_xor_b32_e32 v208, v208, v211
	v_lshlrev_b32_e32 v208, 4, v208
	v_lshl_add_u32 v192, v210, 6, v208
	s_lshr_b32 s74, s73, 1
	s_lshl_b32 s74, s74, 12
	s_and_b32 s75, s73, 1
	s_lshl_b32 s75, s75, 13
	v_add_u32_e32 v194, s75, v192
	v_add_u32_e32 v192, s74, v192
	v_xor_b32_e32 v198, 32, v194
	v_xor_b32_e32 v193, 32, v192
	s_lshl_b32 s74, s73, 16
	s_add_u32 s64, s98, s74
	s_addc_u32 s65, s99, 0
	s_lshl_b32 s74, s73, 12
	s_add_u32 s66, s100, s74
	s_addc_u32 s67, s101, 0
	s_lshl_b32 s68, s73, 11
	s_lshl_b32 s69, s73, 12
	s_mov_b32 s70, 0
	s_mov_b32 s71, 0
	s_mov_b32 s72, 0
	s_waitcnt lgkmcnt(0)
	s_barrier
	s_mul_i32 s74, s70, 0x6000
	s_add_u32 s75, s74, s68
	s_mov_b32 m0, s75
	s_add_u32 s76, s74, 0x2000
	s_cmp_eq_u32 s70, 2
	s_cselect_b32 s76, 0x10000, s76
	global_load_lds_dwordx4 v188, s[64:65]
	s_add_u32 m0, s75, 0x400
	s_add_u32 s76, s76, s69
	global_load_lds_dwordx4 v190, s[64:65]
	s_mov_b32 m0, s76
	s_add_u32 s64, s64, 64
	s_addc_u32 s65, s65, 0
	global_load_lds_dwordx4 v191, s[66:67]
	global_load_lds_dwordx4 v191, s[66:67] offset:1024
	global_load_lds_dwordx4 v191, s[66:67] offset:2048
	global_load_lds_dwordx4 v191, s[66:67] offset:3072
	s_add_u32 s66, s66, 0x10000
	s_addc_u32 s67, s67, 0
	s_add_u32 s70, s70, 1
	s_cmp_eq_u32 s70, 3
	s_cselect_b32 s70, 0, s70
	s_mul_i32 s74, s70, 0x6000
	s_add_u32 s75, s74, s68
	s_mov_b32 m0, s75
	s_add_u32 s76, s74, 0x2000
	s_cmp_eq_u32 s70, 2
	s_cselect_b32 s76, 0x10000, s76
	global_load_lds_dwordx4 v188, s[64:65]
	s_add_u32 m0, s75, 0x400
	s_add_u32 s76, s76, s69
	global_load_lds_dwordx4 v190, s[64:65]
	s_mov_b32 m0, s76
	s_add_u32 s64, s64, 64
	s_addc_u32 s65, s65, 0
	global_load_lds_dwordx4 v191, s[66:67]
	global_load_lds_dwordx4 v191, s[66:67] offset:1024
	global_load_lds_dwordx4 v191, s[66:67] offset:2048
	global_load_lds_dwordx4 v191, s[66:67] offset:3072
	s_add_u32 s66, s66, 0x10000
	s_addc_u32 s67, s67, 0
	s_add_u32 s70, s70, 1
	s_cmp_eq_u32 s70, 3
	s_cselect_b32 s70, 0, s70
	s_cmp_lt_u32 s46, 0x100
	s_cbranch_scc1 .Lp6_nostag
	s_sleep 8

; #define GA_LOAD(pr_) do { _Pragma("unroll") for (int i = 0; i < 4; ++i) ra[i] = *(const u32x4*)(Ab + (i * 32) * lda + (pr_) * 64); } while (0)
; #define GB_LOAD(kt_) do { const bfr* bk_ = Bb + (kt_) * NB * 32; \
;     _Pragma("unroll") for (int i = 0; i < 4; ++i) rb[i] = *(const u32x4*)(bk_ + (i * 64) * 32); } while (0)
; #define G_STORE(kt_) do { bfr* as_ = S0 + ((kt_) & 1) * GSTAGE; bfr* bs_ = as_ + 128 * 40; \
;     if (apar == ((kt_) & 1)) { _Pragma("unroll") for (int i = 0; i < 4; ++i) *(u32x4*)(as_ + asoff + i * 32 * 40) = ra[i]; } \
;     _Pragma("unroll") for (int i = 0; i < 4; ++i) *(u32x4*)(bs_ + bsoff + i * 64 * 40) = rb[i]; } while (0)
; template <int lda>
; DI void gemm_mainloop(const bfr* __restrict__ A, const bfr* __restrict__ Bt, int NB, int K, int m0, int n0, char* smem, f32x16 (&acc)[2][4]) {
;     ...
;   const int nk = K >> 5;
;   const int arow = tid >> 3, ac8 = tid & 7, apar = ac8 >> 2;
;   const bfr* Ab = A + (m0 + arow) * lda + ac8 * 8;
;   const int asoff = arow * 40 + (ac8 & 3) * 8;
;   const int brow = tid >> 2, bc4 = tid & 3;
;   const bfr* Bb = Bt + (n0 + brow) * 32 + bc4 * 8;
;   const int bsoff = brow * 40 + bc4 * 8;
;     ...
;   GA_LOAD(0);
;   GB_LOAD(0);
;   G_STORE(0);
;   GB_LOAD(1);
;   __syncthreads();
; DI void phase_gemm_bf16out(const Params& p, const bfr* A, const bfr* Wt, bfr* C, int N, const float* ss, char* smem) {
;     ...
;   for (int t0 = blockIdx.x; t0 < 128 * ntn; t0 += gridDim.x) {
;     const int t = ((gridDim.x & 7) == 0) ? xcd_tile(t0, ntn) : t0;
;     int mt = t / ntn, nt = t % ntn;
;     gemm_tile<1024>(A, Wt, N, 1024, mt * 128, nt * 256, smem,
.LBB0_925:
	s_ashr_i32 s5, s4, 31
	s_lshr_b32 s5, s5, 30
	s_add_i32 s5, s4, s5
	s_and_b32 s6, s5, 0xfffffc
	s_lshl_b32 s5, s5, 5
	s_and_b32 s30, s5, 0xffffff80
	s_sub_i32 s4, s4, s6
	s_lshl_b32 s29, s4, 8
	s_mov_b32 s31, 0
	s_mov_b64 s[6:7], 0
	s_cmp_lt_u32 s46, 0x100
	s_cselect_b32 s98, 0, 0x100
	s_xor_b32 s29, s29, s98
	s_lshl_b32 s98, s30, 11
	s_add_u32 s98, s10, s98
	s_addc_u32 s99, s11, 0
	s_lshl_b32 s100, s29, 6
	s_add_u32 s100, s12, s100
	s_addc_u32 s101, s13, 0
	v_writelane_b32 v187, s64, 0
	v_writelane_b32 v187, s65, 1
	v_writelane_b32 v187, s66, 2
	v_writelane_b32 v187, s67, 3
	v_writelane_b32 v187, s68, 4
	v_writelane_b32 v187, s69, 5
	v_writelane_b32 v187, s70, 6
	v_writelane_b32 v187, s71, 7
	v_writelane_b32 v187, s72, 8
	v_writelane_b32 v187, s73, 9
	v_writelane_b32 v187, s74, 10
	v_writelane_b32 v187, s75, 11
	v_writelane_b32 v187, s76, 12
	v_writelane_b32 v187, s77, 13
	v_writelane_b32 v187, s78, 14
	v_writelane_b32 v187, s79, 15
	s_mov_b32 s77, s30
	s_mov_b32 s78, s29
	v_lshrrev_b32_e32 v188, 6, v196
	v_and_b32_e32 v189, 63, v196
	v_readfirstlane_b32 s73, v188
	v_lshrrev_b32_e32 v190, 2, v189
	v_bfe_u32 v191, v189, 4, 2
	v_and_b32_e32 v188, 3, v189
	v_xor_b32_e32 v188, v188, v191
	v_lshlrev_b32_e32 v188, 4, v188
	v_lshl_add_u32 v176, v190, 11, v188
	v_add_u32_e32 v177, 0x8000, v176
	v_lshl_add_u32 v178, v190, 6, v188
	v_and_b32_e32 v190, 31, v189
	v_lshrrev_b32_e32 v191, 5, v189
	v_bfe_u32 v188, v189, 2, 2
	v_xor_b32_e32 v188, v188, v191
	v_lshlrev_b32_e32 v188, 4, v188
	v_lshl_add_u32 v179, v190, 6, v188
	s_lshr_b32 s74, s73, 1
	s_lshl_b32 s74, s74, 12
	s_and_b32 s75, s73, 1
	s_lshl_b32 s75, s75, 13
	v_add_u32_e32 v181, s75, v179
	v_add_u32_e32 v179, s74, v179
	v_xor_b32_e32 v182, 32, v181
	v_xor_b32_e32 v180, 32, v179
	s_lshl_b32 s74, s73, 16
	s_add_u32 s64, s98, s74
	s_addc_u32 s65, s99, 0
	s_lshl_b32 s74, s73, 12
	s_add_u32 s66, s100, s74
	s_addc_u32 s67, s101, 0
	s_lshl_b32 s68, s73, 11
	s_lshl_b32 s69, s73, 12
	s_mov_b32 s70, 0
	s_mov_b32 s71, 0
	s_mov_b32 s72, 0
	s_waitcnt lgkmcnt(0)
	s_barrier
	s_mul_i32 s74, s70, 0x6000
	s_add_u32 s75, s74, s68
	s_mov_b32 m0, s75
	s_add_u32 s76, s74, 0x2000
	s_cmp_eq_u32 s70, 2
	s_cselect_b32 s76, 0x10000, s76
	global_load_lds_dwordx4 v176, s[64:65]
	s_add_u32 m0, s75, 0x400
	s_add_u32 s76, s76, s69
	global_load_lds_dwordx4 v177, s[64:65]
	s_mov_b32 m0, s76
	s_add_u32 s64, s64, 64
	s_addc_u32 s65, s65, 0
	global_load_lds_dwordx4 v178, s[66:67]
	global_load_lds_dwordx4 v178, s[66:67] offset:1024
	global_load_lds_dwordx4 v178, s[66:67] offset:2048
	global_load_lds_dwordx4 v178, s[66:67] offset:3072
	s_add_u32 s66, s66, 0x10000
	s_addc_u32 s67, s67, 0
	s_add_u32 s70, s70, 1
	s_cmp_eq_u32 s70, 3
	s_cselect_b32 s70, 0, s70
	s_mul_i32 s74, s70, 0x6000
	s_add_u32 s75, s74, s68
	s_mov_b32 m0, s75
	s_add_u32 s76, s74, 0x2000
	s_cmp_eq_u32 s70, 2
	s_cselect_b32 s76, 0x10000, s76
	global_load_lds_dwordx4 v176, s[64:65]
	s_add_u32 m0, s75, 0x400
	s_add_u32 s76, s76, s69
	global_load_lds_dwordx4 v177, s[64:65]
	s_mov_b32 m0, s76
	s_add_u32 s64, s64, 64
	s_addc_u32 s65, s65, 0
	global_load_lds_dwordx4 v178, s[66:67]
	global_load_lds_dwordx4 v178, s[66:67] offset:1024
	global_load_lds_dwordx4 v178, s[66:67] offset:2048
	global_load_lds_dwordx4 v178, s[66:67] offset:3072
	s_add_u32 s66, s66, 0x10000
	s_addc_u32 s67, s67, 0
	s_add_u32 s70, s70, 1
	s_cmp_eq_u32 s70, 3
	s_cselect_b32 s70, 0, s70
	s_cmp_lt_u32 s46, 0x100
	s_cbranch_scc1 .Lp8_nostag
	s_sleep 8

; #define GA_LOAD(pr_) do { _Pragma("unroll") for (int i = 0; i < 4; ++i) ra[i] = *(const u32x4*)(Ab + (i * 32) * lda + (pr_) * 64); } while (0)
; #define GB_LOAD(kt_) do { const bfr* bk_ = Bb + (kt_) * NB * 32; \
;     _Pragma("unroll") for (int i = 0; i < 4; ++i) rb[i] = *(const u32x4*)(bk_ + (i * 64) * 32); } while (0)
; #define G_STORE(kt_) do { bfr* as_ = S0 + ((kt_) & 1) * GSTAGE; bfr* bs_ = as_ + 128 * 40; \
;     if (apar == ((kt_) & 1)) { _Pragma("unroll") for (int i = 0; i < 4; ++i) *(u32x4*)(as_ + asoff + i * 32 * 40) = ra[i]; } \
;     _Pragma("unroll") for (int i = 0; i < 4; ++i) *(u32x4*)(bs_ + bsoff + i * 64 * 40) = rb[i]; } while (0)
; template <int lda>
; DI void gemm_mainloop(const bfr* __restrict__ A, const bfr* __restrict__ Bt, int NB, int K, int m0, int n0, char* smem, f32x16 (&acc)[2][4]) {
;     ...
;   const int nk = K >> 5;
;   const int arow = tid >> 3, ac8 = tid & 7, apar = ac8 >> 2;
;   const bfr* Ab = A + (m0 + arow) * lda + ac8 * 8;
;   const int asoff = arow * 40 + (ac8 & 3) * 8;
;   const int brow = tid >> 2, bc4 = tid & 3;
;   const bfr* Bb = Bt + (n0 + brow) * 32 + bc4 * 8;
;   const int bsoff = brow * 40 + bc4 * 8;
;     ...
;   GA_LOAD(0);
;   GB_LOAD(0);
;   G_STORE(0);
;   GB_LOAD(1);
;   __syncthreads();
; template <bool FIRST, bool HAS_H>
; DI void phase_gemm_resid(const Params& p, const bfr* A, const bfr* Wt, const float* gnext, float* ss, char* smem) {
;     ...
;   for (int t0 = blockIdx.x; t0 < 128 * 4; t0 += gridDim.x) {
;     const int t = ((gridDim.x & 7) == 0) ? xcd_tile(t0, 4) : t0;
;     const int mt = t >> 2, nt = t & 3, m0 = mt * 128, n0 = nt * 256;
;     f32x16 acc[2][4];
;     gemm_mainloop<1024>(A, Wt, 1024, 1024, m0, n0, smem, acc);
.LBB0_1099:
	s_lshl_b32 s5, s4, 5
	s_and_b32 s36, s5, 0xffffff80
	s_lshl_b32 s4, s4, 8
	s_and_b32 s33, s4, 0x300
	s_mov_b32 s37, 0
	s_mov_b64 s[20:21], 0
	s_cmp_lt_u32 s46, 0x100
	s_cselect_b32 s98, 0, 0x100
	s_xor_b32 s33, s33, s98
	s_lshl_b32 s98, s36, 11
	s_add_u32 s98, s2, s98
	s_addc_u32 s99, s3, 0
	s_lshl_b32 s100, s33, 6
	s_add_u32 s100, s8, s100
	s_addc_u32 s101, s9, 0
	v_writelane_b32 v207, s64, 0
	v_writelane_b32 v207, s65, 1
	v_writelane_b32 v207, s66, 2
	v_writelane_b32 v207, s67, 3
	v_writelane_b32 v207, s68, 4
	v_writelane_b32 v207, s69, 5
	v_writelane_b32 v207, s70, 6
	v_writelane_b32 v207, s71, 7
	v_writelane_b32 v207, s72, 8
	v_writelane_b32 v207, s73, 9
	v_writelane_b32 v207, s74, 10
	v_writelane_b32 v207, s75, 11
	v_writelane_b32 v207, s76, 12
	v_writelane_b32 v207, s77, 13
	v_writelane_b32 v207, s78, 14
	v_writelane_b32 v207, s79, 15
	s_mov_b32 s77, s36
	s_mov_b32 s78, s33
	v_lshrrev_b32_e32 v208, 6, v196
	v_and_b32_e32 v209, 63, v196
	v_readfirstlane_b32 s73, v208
	v_lshrrev_b32_e32 v210, 2, v209
	v_bfe_u32 v211, v209, 4, 2
	v_and_b32_e32 v208, 3, v209
	v_xor_b32_e32 v208, v208, v211
	v_lshlrev_b32_e32 v208, 4, v208
	v_lshl_add_u32 v192, v210, 11, v208
	v_add_u32_e32 v194, 0x8000, v192
	v_lshl_add_u32 v198, v210, 6, v208
	v_and_b32_e32 v210, 31, v209
	v_lshrrev_b32_e32 v211, 5, v209
	v_bfe_u32 v208, v209, 2, 2
	v_xor_b32_e32 v208, v208, v211
	v_lshlrev_b32_e32 v208, 4, v208
	v_lshl_add_u32 v199, v210, 6, v208
	s_lshr_b32 s74, s73, 1
	s_lshl_b32 s74, s74, 12
	s_and_b32 s75, s73, 1
	s_lshl_b32 s75, s75, 13
	v_add_u32_e32 v201, s75, v199
	v_add_u32_e32 v199, s74, v199
	v_xor_b32_e32 v202, 32, v201
	v_xor_b32_e32 v200, 32, v199
	s_lshl_b32 s74, s73, 16
	s_add_u32 s64, s98, s74
	s_addc_u32 s65, s99, 0
	s_lshl_b32 s74, s73, 12
	s_add_u32 s66, s100, s74
	s_addc_u32 s67, s101, 0
	s_lshl_b32 s68, s73, 11
	s_lshl_b32 s69, s73, 12
	s_mov_b32 s70, 0
	s_mov_b32 s71, 0
	s_mov_b32 s72, 0
	s_waitcnt lgkmcnt(0)
	s_barrier
	s_mul_i32 s74, s70, 0x6000
	s_add_u32 s75, s74, s68
	s_mov_b32 m0, s75
	s_add_u32 s76, s74, 0x2000
	s_cmp_eq_u32 s70, 2
	s_cselect_b32 s76, 0x10000, s76
	global_load_lds_dwordx4 v192, s[64:65]
	s_add_u32 m0, s75, 0x400
	s_add_u32 s76, s76, s69
	global_load_lds_dwordx4 v194, s[64:65]
	s_mov_b32 m0, s76
	s_add_u32 s64, s64, 64
	s_addc_u32 s65, s65, 0
	global_load_lds_dwordx4 v198, s[66:67]
	global_load_lds_dwordx4 v198, s[66:67] offset:1024
	global_load_lds_dwordx4 v198, s[66:67] offset:2048
	global_load_lds_dwordx4 v198, s[66:67] offset:3072
	s_add_u32 s66, s66, 0x10000
	s_addc_u32 s67, s67, 0
	s_add_u32 s70, s70, 1
	s_cmp_eq_u32 s70, 3
	s_cselect_b32 s70, 0, s70
	s_mul_i32 s74, s70, 0x6000
	s_add_u32 s75, s74, s68
	s_mov_b32 m0, s75
	s_add_u32 s76, s74, 0x2000
	s_cmp_eq_u32 s70, 2
	s_cselect_b32 s76, 0x10000, s76
	global_load_lds_dwordx4 v192, s[64:65]
	s_add_u32 m0, s75, 0x400
	s_add_u32 s76, s76, s69
	global_load_lds_dwordx4 v194, s[64:65]
	s_mov_b32 m0, s76
	s_add_u32 s64, s64, 64
	s_addc_u32 s65, s65, 0
	global_load_lds_dwordx4 v198, s[66:67]
	global_load_lds_dwordx4 v198, s[66:67] offset:1024
	global_load_lds_dwordx4 v198, s[66:67] offset:2048
	global_load_lds_dwordx4 v198, s[66:67] offset:3072
	s_add_u32 s66, s66, 0x10000
	s_addc_u32 s67, s67, 0
	s_add_u32 s70, s70, 1
	s_cmp_eq_u32 s70, 3
	s_cselect_b32 s70, 0, s70
	s_cmp_lt_u32 s46, 0x100
	s_cbranch_scc1 .Lp10_nostag
	s_sleep 8

; #define GA_LOAD(pr_) do { _Pragma("unroll") for (int i = 0; i < 4; ++i) ra[i] = *(const u32x4*)(Ab + (i * 32) * lda + (pr_) * 64); } while (0)
; #define GB_LOAD(kt_) do { const bfr* bk_ = Bb + (kt_) * NB * 32; \
;     _Pragma("unroll") for (int i = 0; i < 4; ++i) rb[i] = *(const u32x4*)(bk_ + (i * 64) * 32); } while (0)
; #define G_STORE(kt_) do { bfr* as_ = S0 + ((kt_) & 1) * GSTAGE; bfr* bs_ = as_ + 128 * 40; \
;     if (apar == ((kt_) & 1)) { _Pragma("unroll") for (int i = 0; i < 4; ++i) *(u32x4*)(as_ + asoff + i * 32 * 40) = ra[i]; } \
;     _Pragma("unroll") for (int i = 0; i < 4; ++i) *(u32x4*)(bs_ + bsoff + i * 64 * 40) = rb[i]; } while (0)
; template <int lda>
; DI void gemm_mainloop(const bfr* __restrict__ A, const bfr* __restrict__ Bt, int NB, int K, int m0, int n0, char* smem, f32x16 (&acc)[2][4]) {
;     ...
;   const int nk = K >> 5;
;   const int arow = tid >> 3, ac8 = tid & 7, apar = ac8 >> 2;
;   const bfr* Ab = A + (m0 + arow) * lda + ac8 * 8;
;   const int asoff = arow * 40 + (ac8 & 3) * 8;
;   const int brow = tid >> 2, bc4 = tid & 3;
;   const bfr* Bb = Bt + (n0 + brow) * 32 + bc4 * 8;
;   const int bsoff = brow * 40 + bc4 * 8;
;     ...
;   GA_LOAD(0);
;   GB_LOAD(0);
;   G_STORE(0);
;   GB_LOAD(1);
;   __syncthreads();
; template <bool FIRST, bool HAS_H>
; DI void phase_gemm_resid(const Params& p, const bfr* A, const bfr* Wt, const float* gnext, float* ss, char* smem) {
;     ...
;   for (int t0 = blockIdx.x; t0 < 128 * 4; t0 += gridDim.x) {
;     const int t = ((gridDim.x & 7) == 0) ? xcd_tile(t0, 4) : t0;
;     const int mt = t >> 2, nt = t & 3, m0 = mt * 128, n0 = nt * 256;
;     f32x16 acc[2][4];
;     gemm_mainloop<1024>(A, Wt, 1024, 1024, m0, n0, smem, acc);
.LBB0_1466:
	s_lshl_b32 s5, s4, 5
	s_and_b32 s36, s5, 0xffffff80
	s_lshl_b32 s4, s4, 8
	s_and_b32 s33, s4, 0x300
	s_mov_b32 s37, 0
	s_mov_b64 s[20:21], 0
	s_cmp_lt_u32 s46, 0x100
	s_cselect_b32 s98, 0, 0x100
	s_xor_b32 s33, s33, s98
	s_lshl_b32 s98, s36, 11
	s_add_u32 s98, s2, s98
	s_addc_u32 s99, s3, 0
	s_lshl_b32 s100, s33, 6
	s_add_u32 s100, s8, s100
	s_addc_u32 s101, s9, 0
	v_writelane_b32 v209, s64, 0
	v_writelane_b32 v209, s65, 1
	v_writelane_b32 v209, s66, 2
	v_writelane_b32 v209, s67, 3
	v_writelane_b32 v209, s68, 4
	v_writelane_b32 v209, s69, 5
	v_writelane_b32 v209, s70, 6
	v_writelane_b32 v209, s71, 7
	v_writelane_b32 v209, s72, 8
	v_writelane_b32 v209, s73, 9
	v_writelane_b32 v209, s74, 10
	v_writelane_b32 v209, s75, 11
	v_writelane_b32 v209, s76, 12
	v_writelane_b32 v209, s77, 13
	v_writelane_b32 v209, s78, 14
	v_writelane_b32 v209, s79, 15
	s_mov_b32 s77, s36
	s_mov_b32 s78, s33
	v_lshrrev_b32_e32 v210, 6, v196
	v_and_b32_e32 v211, 63, v196
	v_readfirstlane_b32 s73, v210
	v_lshrrev_b32_e32 v216, 2, v211
	v_bfe_u32 v217, v211, 4, 2
	v_and_b32_e32 v210, 3, v211
	v_xor_b32_e32 v210, v210, v217
	v_lshlrev_b32_e32 v210, 4, v210
	v_lshl_add_u32 v192, v216, 11, v210
	v_add_u32_e32 v194, 0x8000, v192
	v_lshl_add_u32 v200, v216, 6, v210
	v_and_b32_e32 v216, 31, v211
	v_lshrrev_b32_e32 v217, 5, v211
	v_bfe_u32 v210, v211, 2, 2
	v_xor_b32_e32 v210, v210, v217
	v_lshlrev_b32_e32 v210, 4, v210
	v_lshl_add_u32 v201, v216, 6, v210
	s_lshr_b32 s74, s73, 1
	s_lshl_b32 s74, s74, 12
	s_and_b32 s75, s73, 1
	s_lshl_b32 s75, s75, 13
	v_add_u32_e32 v203, s75, v201
	v_add_u32_e32 v201, s74, v201
	v_xor_b32_e32 v204, 32, v203
	v_xor_b32_e32 v202, 32, v201
	s_lshl_b32 s74, s73, 16
	s_add_u32 s64, s98, s74
	s_addc_u32 s65, s99, 0
	s_lshl_b32 s74, s73, 12
	s_add_u32 s66, s100, s74
	s_addc_u32 s67, s101, 0
	s_lshl_b32 s68, s73, 11
	s_lshl_b32 s69, s73, 12
	s_mov_b32 s70, 0
	s_mov_b32 s71, 0
	s_mov_b32 s72, 0
	s_waitcnt lgkmcnt(0)
	s_barrier
	s_mul_i32 s74, s70, 0x6000
	s_add_u32 s75, s74, s68
	s_mov_b32 m0, s75
	s_add_u32 s76, s74, 0x2000
	s_cmp_eq_u32 s70, 2
	s_cselect_b32 s76, 0x10000, s76
	global_load_lds_dwordx4 v192, s[64:65]
	s_add_u32 m0, s75, 0x400
	s_add_u32 s76, s76, s69
	global_load_lds_dwordx4 v194, s[64:65]
	s_mov_b32 m0, s76
	s_add_u32 s64, s64, 64
	s_addc_u32 s65, s65, 0
	global_load_lds_dwordx4 v200, s[66:67]
	global_load_lds_dwordx4 v200, s[66:67] offset:1024
	global_load_lds_dwordx4 v200, s[66:67] offset:2048
	global_load_lds_dwordx4 v200, s[66:67] offset:3072
	s_add_u32 s66, s66, 0x10000
	s_addc_u32 s67, s67, 0
	s_add_u32 s70, s70, 1
	s_cmp_eq_u32 s70, 3
	s_cselect_b32 s70, 0, s70
	s_mul_i32 s74, s70, 0x6000
	s_add_u32 s75, s74, s68
	s_mov_b32 m0, s75
	s_add_u32 s76, s74, 0x2000
	s_cmp_eq_u32 s70, 2
	s_cselect_b32 s76, 0x10000, s76
	global_load_lds_dwordx4 v192, s[64:65]
	s_add_u32 m0, s75, 0x400
	s_add_u32 s76, s76, s69
	global_load_lds_dwordx4 v194, s[64:65]
	s_mov_b32 m0, s76
	s_add_u32 s64, s64, 64
	s_addc_u32 s65, s65, 0
	global_load_lds_dwordx4 v200, s[66:67]
	global_load_lds_dwordx4 v200, s[66:67] offset:1024
	global_load_lds_dwordx4 v200, s[66:67] offset:2048
	global_load_lds_dwordx4 v200, s[66:67] offset:3072
	s_add_u32 s66, s66, 0x10000
	s_addc_u32 s67, s67, 0
	s_add_u32 s70, s70, 1
	s_cmp_eq_u32 s70, 3
	s_cselect_b32 s70, 0, s70
	s_cmp_lt_u32 s46, 0x100
	s_cbranch_scc1 .Lp15_nostag
	s_sleep 8

; #define GA_LOAD(pr_) do { _Pragma("unroll") for (int i = 0; i < 4; ++i) ra[i] = *(const u32x4*)(Ab + (i * 32) * lda + (pr_) * 64); } while (0)
; #define GB_LOAD(kt_) do { const bfr* bk_ = Bb + (kt_) * NB * 32; \
;     _Pragma("unroll") for (int i = 0; i < 4; ++i) rb[i] = *(const u32x4*)(bk_ + (i * 64) * 32); } while (0)
; #define G_STORE(kt_) do { bfr* as_ = S0 + ((kt_) & 1) * GSTAGE; bfr* bs_ = as_ + 128 * 40; \
;     if (apar == ((kt_) & 1)) { _Pragma("unroll") for (int i = 0; i < 4; ++i) *(u32x4*)(as_ + asoff + i * 32 * 40) = ra[i]; } \
;     _Pragma("unroll") for (int i = 0; i < 4; ++i) *(u32x4*)(bs_ + bsoff + i * 64 * 40) = rb[i]; } while (0)
; template <int lda>
; DI void gemm_mainloop(const bfr* __restrict__ A, const bfr* __restrict__ Bt, int NB, int K, int m0, int n0, char* smem, f32x16 (&acc)[2][4]) {
;     ...
;   const int nk = K >> 5;
;   const int arow = tid >> 3, ac8 = tid & 7, apar = ac8 >> 2;
;   const bfr* Ab = A + (m0 + arow) * lda + ac8 * 8;
;   const int asoff = arow * 40 + (ac8 & 3) * 8;
;   const int brow = tid >> 2, bc4 = tid & 3;
;   const bfr* Bb = Bt + (n0 + brow) * 32 + bc4 * 8;
;   const int bsoff = brow * 40 + bc4 * 8;
;     ...
;   GA_LOAD(0);
;   GB_LOAD(0);
;   G_STORE(0);
;   GB_LOAD(1);
;   __syncthreads();
; DI void phase_gemm_bf16out(const Params& p, const bfr* A, const bfr* Wt, bfr* C, int N, const float* ss, char* smem) {
;     ...
;   for (int t0 = blockIdx.x; t0 < 128 * ntn; t0 += gridDim.x) {
;     const int t = ((gridDim.x & 7) == 0) ? xcd_tile(t0, ntn) : t0;
;     int mt = t / ntn, nt = t % ntn;
;     gemm_tile<1024>(A, Wt, N, 1024, mt * 128, nt * 256, smem,
.LBB0_1548:
	s_ashr_i32 s5, s4, 31
	s_lshr_b32 s5, s5, 30
	s_add_i32 s5, s4, s5
	s_and_b32 s20, s5, 0xfffffc
	s_lshl_b32 s5, s5, 5
	s_and_b32 s33, s5, 0xffffff80
	s_sub_i32 s4, s4, s20
	s_lshl_b32 s31, s4, 8
	s_mov_b32 s36, 0
	s_mov_b64 s[20:21], 0
	s_cmp_lt_u32 s46, 0x100
	s_cselect_b32 s98, 0, 0x100
	s_xor_b32 s31, s31, s98
	s_lshl_b32 s98, s33, 11
	s_add_u32 s98, s10, s98
	s_addc_u32 s99, s11, 0
	s_lshl_b32 s100, s31, 6
	s_add_u32 s100, s14, s100
	s_addc_u32 s101, s15, 0
	v_writelane_b32 v187, s64, 0
	v_writelane_b32 v187, s65, 1
	v_writelane_b32 v187, s66, 2
	v_writelane_b32 v187, s67, 3
	v_writelane_b32 v187, s68, 4
	v_writelane_b32 v187, s69, 5
	v_writelane_b32 v187, s70, 6
	v_writelane_b32 v187, s71, 7
	v_writelane_b32 v187, s72, 8
	v_writelane_b32 v187, s73, 9
	v_writelane_b32 v187, s74, 10
	v_writelane_b32 v187, s75, 11
	v_writelane_b32 v187, s76, 12
	v_writelane_b32 v187, s77, 13
	v_writelane_b32 v187, s78, 14
	v_writelane_b32 v187, s79, 15
	s_mov_b32 s77, s33
	s_mov_b32 s78, s31
	v_lshrrev_b32_e32 v188, 6, v196
	v_and_b32_e32 v189, 63, v196
	v_readfirstlane_b32 s73, v188
	v_lshrrev_b32_e32 v190, 2, v189
	v_bfe_u32 v191, v189, 4, 2
	v_and_b32_e32 v188, 3, v189
	v_xor_b32_e32 v188, v188, v191
	v_lshlrev_b32_e32 v188, 4, v188
	v_lshl_add_u32 v176, v190, 11, v188
	v_add_u32_e32 v177, 0x8000, v176
	v_lshl_add_u32 v178, v190, 6, v188
	v_and_b32_e32 v190, 31, v189
	v_lshrrev_b32_e32 v191, 5, v189
	v_bfe_u32 v188, v189, 2, 2
	v_xor_b32_e32 v188, v188, v191
	v_lshlrev_b32_e32 v188, 4, v188
	v_lshl_add_u32 v179, v190, 6, v188
	s_lshr_b32 s74, s73, 1
	s_lshl_b32 s74, s74, 12
	s_and_b32 s75, s73, 1
	s_lshl_b32 s75, s75, 13
	v_add_u32_e32 v181, s75, v179
	v_add_u32_e32 v179, s74, v179
	v_xor_b32_e32 v182, 32, v181
	v_xor_b32_e32 v180, 32, v179
	s_lshl_b32 s74, s73, 16
	s_add_u32 s64, s98, s74
	s_addc_u32 s65, s99, 0
	s_lshl_b32 s74, s73, 12
	s_add_u32 s66, s100, s74
	s_addc_u32 s67, s101, 0
	s_lshl_b32 s68, s73, 11
	s_lshl_b32 s69, s73, 12
	s_mov_b32 s70, 0
	s_mov_b32 s71, 0
	s_mov_b32 s72, 0
	s_waitcnt lgkmcnt(0)
	s_barrier
	s_mul_i32 s74, s70, 0x6000
	s_add_u32 s75, s74, s68
	s_mov_b32 m0, s75
	s_add_u32 s76, s74, 0x2000
	s_cmp_eq_u32 s70, 2
	s_cselect_b32 s76, 0x10000, s76
	global_load_lds_dwordx4 v176, s[64:65]
	s_add_u32 m0, s75, 0x400
	s_add_u32 s76, s76, s69
	global_load_lds_dwordx4 v177, s[64:65]
	s_mov_b32 m0, s76
	s_add_u32 s64, s64, 64
	s_addc_u32 s65, s65, 0
	global_load_lds_dwordx4 v178, s[66:67]
	global_load_lds_dwordx4 v178, s[66:67] offset:1024
	global_load_lds_dwordx4 v178, s[66:67] offset:2048
	global_load_lds_dwordx4 v178, s[66:67] offset:3072
	s_add_u32 s66, s66, 0x10000
	s_addc_u32 s67, s67, 0
	s_add_u32 s70, s70, 1
	s_cmp_eq_u32 s70, 3
	s_cselect_b32 s70, 0, s70
	s_mul_i32 s74, s70, 0x6000
	s_add_u32 s75, s74, s68
	s_mov_b32 m0, s75
	s_add_u32 s76, s74, 0x2000
	s_cmp_eq_u32 s70, 2
	s_cselect_b32 s76, 0x10000, s76
	global_load_lds_dwordx4 v176, s[64:65]
	s_add_u32 m0, s75, 0x400
	s_add_u32 s76, s76, s69
	global_load_lds_dwordx4 v177, s[64:65]
	s_mov_b32 m0, s76
	s_add_u32 s64, s64, 64
	s_addc_u32 s65, s65, 0
	global_load_lds_dwordx4 v178, s[66:67]
	global_load_lds_dwordx4 v178, s[66:67] offset:1024
	global_load_lds_dwordx4 v178, s[66:67] offset:2048
	global_load_lds_dwordx4 v178, s[66:67] offset:3072
	s_add_u32 s66, s66, 0x10000
	s_addc_u32 s67, s67, 0
	s_add_u32 s70, s70, 1
	s_cmp_eq_u32 s70, 3
	s_cselect_b32 s70, 0, s70
	s_cmp_lt_u32 s46, 0x100
	s_cbranch_scc1 .Lp17_nostag
	s_sleep 8

; #define GA_LOAD(pr_) do { _Pragma("unroll") for (int i = 0; i < 4; ++i) ra[i] = *(const u32x4*)(Ab + (i * 32) * lda + (pr_) * 64); } while (0)
; #define GB_LOAD(kt_) do { const bfr* bk_ = Bb + (kt_) * NB * 32; \
;     _Pragma("unroll") for (int i = 0; i < 4; ++i) rb[i] = *(const u32x4*)(bk_ + (i * 64) * 32); } while (0)
; #define G_STORE(kt_) do { bfr* as_ = S0 + ((kt_) & 1) * GSTAGE; bfr* bs_ = as_ + 128 * 40; \
;     if (apar == ((kt_) & 1)) { _Pragma("unroll") for (int i = 0; i < 4; ++i) *(u32x4*)(as_ + asoff + i * 32 * 40) = ra[i]; } \
;     _Pragma("unroll") for (int i = 0; i < 4; ++i) *(u32x4*)(bs_ + bsoff + i * 64 * 40) = rb[i]; } while (0)
; template <int lda>
; DI void gemm_mainloop(const bfr* __restrict__ A, const bfr* __restrict__ Bt, int NB, int K, int m0, int n0, char* smem, f32x16 (&acc)[2][4]) {
;     ...
;   const int nk = K >> 5;
;   const int arow = tid >> 3, ac8 = tid & 7, apar = ac8 >> 2;
;   const bfr* Ab = A + (m0 + arow) * lda + ac8 * 8;
;   const int asoff = arow * 40 + (ac8 & 3) * 8;
;   const int brow = tid >> 2, bc4 = tid & 3;
;   const bfr* Bb = Bt + (n0 + brow) * 32 + bc4 * 8;
;   const int bsoff = brow * 40 + bc4 * 8;
;     ...
;   GA_LOAD(0);
;   GB_LOAD(0);
;   G_STORE(0);
;   GB_LOAD(1);
;   __syncthreads();
; template <bool FIRST, bool HAS_H>
; DI void phase_gemm_resid(const Params& p, const bfr* A, const bfr* Wt, const float* gnext, float* ss, char* smem) {
;     ...
;   for (int t0 = blockIdx.x; t0 < 128 * 4; t0 += gridDim.x) {
;     const int t = ((gridDim.x & 7) == 0) ? xcd_tile(t0, 4) : t0;
;     const int mt = t >> 2, nt = t & 3, m0 = mt * 128, n0 = nt * 256;
;     f32x16 acc[2][4];
;     gemm_mainloop<1024>(A, Wt, 1024, 1024, m0, n0, smem, acc);
.LBB0_1721:
	s_lshl_b32 s5, s4, 5
	s_and_b32 s59, s5, 0xffffff80
	s_lshl_b32 s4, s4, 8
	s_and_b32 s58, s4, 0x300
	s_mov_b32 s60, 0
	s_mov_b64 s[16:17], 0
	s_cmp_lt_u32 s46, 0x100
	s_cselect_b32 s98, 0, 0x100
	s_xor_b32 s58, s58, s98
	s_lshl_b32 s98, s59, 11
	s_add_u32 s98, s6, s98
	s_addc_u32 s99, s7, 0
	s_lshl_b32 s100, s58, 6
	s_add_u32 s100, s2, s100
	s_addc_u32 s101, s3, 0
	v_writelane_b32 v209, s64, 0
	v_writelane_b32 v209, s65, 1
	v_writelane_b32 v209, s66, 2
	v_writelane_b32 v209, s67, 3
	v_writelane_b32 v209, s68, 4
	v_writelane_b32 v209, s69, 5
	v_writelane_b32 v209, s70, 6
	v_writelane_b32 v209, s71, 7
	v_writelane_b32 v209, s72, 8
	v_writelane_b32 v209, s73, 9
	v_writelane_b32 v209, s74, 10
	v_writelane_b32 v209, s75, 11
	v_writelane_b32 v209, s76, 12
	v_writelane_b32 v209, s77, 13
	v_writelane_b32 v209, s78, 14
	v_writelane_b32 v209, s79, 15
	s_mov_b32 s77, s59
	s_mov_b32 s78, s58
	v_lshrrev_b32_e32 v210, 6, v196
	v_and_b32_e32 v211, 63, v196
	v_readfirstlane_b32 s73, v210
	v_lshrrev_b32_e32 v212, 2, v211
	v_bfe_u32 v213, v211, 4, 2
	v_and_b32_e32 v210, 3, v211
	v_xor_b32_e32 v210, v210, v213
	v_lshlrev_b32_e32 v210, 4, v210
	v_lshl_add_u32 v180, v212, 11, v210
	v_add_u32_e32 v182, 0x8000, v180
	v_lshl_add_u32 v183, v212, 6, v210
	v_and_b32_e32 v212, 31, v211
	v_lshrrev_b32_e32 v213, 5, v211
	v_bfe_u32 v210, v211, 2, 2
	v_xor_b32_e32 v210, v210, v213
	v_lshlrev_b32_e32 v210, 4, v210
	v_lshl_add_u32 v192, v212, 6, v210
	s_lshr_b32 s74, s73, 1
	s_lshl_b32 s74, s74, 12
	s_and_b32 s75, s73, 1
	s_lshl_b32 s75, s75, 13
	v_add_u32_e32 v194, s75, v192
	v_add_u32_e32 v192, s74, v192
	v_xor_b32_e32 v204, 32, v194
	v_xor_b32_e32 v193, 32, v192
	s_lshl_b32 s74, s73, 16
	s_add_u32 s64, s98, s74
	s_addc_u32 s65, s99, 0
	s_lshl_b32 s74, s73, 12
	s_add_u32 s66, s100, s74
	s_addc_u32 s67, s101, 0
	s_lshl_b32 s68, s73, 11
	s_lshl_b32 s69, s73, 12
	s_mov_b32 s70, 0
	s_mov_b32 s71, 0
	s_mov_b32 s72, 0
	s_waitcnt lgkmcnt(0)
	s_barrier
	s_mul_i32 s74, s70, 0x6000
	s_add_u32 s75, s74, s68
	s_mov_b32 m0, s75
	s_add_u32 s76, s74, 0x2000
	s_cmp_eq_u32 s70, 2
	s_cselect_b32 s76, 0x10000, s76
	global_load_lds_dwordx4 v180, s[64:65]
	s_add_u32 m0, s75, 0x400
	s_add_u32 s76, s76, s69
	global_load_lds_dwordx4 v182, s[64:65]
	s_mov_b32 m0, s76
	s_add_u32 s64, s64, 64
	s_addc_u32 s65, s65, 0
	global_load_lds_dwordx4 v183, s[66:67]
	global_load_lds_dwordx4 v183, s[66:67] offset:1024
	global_load_lds_dwordx4 v183, s[66:67] offset:2048
	global_load_lds_dwordx4 v183, s[66:67] offset:3072
	s_add_u32 s66, s66, 0x10000
	s_addc_u32 s67, s67, 0
	s_add_u32 s70, s70, 1
	s_cmp_eq_u32 s70, 3
	s_cselect_b32 s70, 0, s70
	s_mul_i32 s74, s70, 0x6000
	s_add_u32 s75, s74, s68
	s_mov_b32 m0, s75
	s_add_u32 s76, s74, 0x2000
	s_cmp_eq_u32 s70, 2
	s_cselect_b32 s76, 0x10000, s76
	global_load_lds_dwordx4 v180, s[64:65]
	s_add_u32 m0, s75, 0x400
	s_add_u32 s76, s76, s69
	global_load_lds_dwordx4 v182, s[64:65]
	s_mov_b32 m0, s76
	s_add_u32 s64, s64, 64
	s_addc_u32 s65, s65, 0
	global_load_lds_dwordx4 v183, s[66:67]
	global_load_lds_dwordx4 v183, s[66:67] offset:1024
	global_load_lds_dwordx4 v183, s[66:67] offset:2048
	global_load_lds_dwordx4 v183, s[66:67] offset:3072
	s_add_u32 s66, s66, 0x10000
	s_addc_u32 s67, s67, 0
	s_add_u32 s70, s70, 1
	s_cmp_eq_u32 s70, 3
	s_cselect_b32 s70, 0, s70
	s_cmp_lt_u32 s46, 0x100
	s_cbranch_scc1 .Lp19_nostag
	s_sleep 8
